# GEMM K-loops: next-tile loads spread one per two MFMAs across ks0-ks2 (lighter MFMA gaps than one per MFMA)
# speedup vs baseline: 1.0544x; 1.0052x over previous
; DI unsigned swz(int row, int chunk) { return (unsigned)row * 128u + (unsigned)((chunk ^ ((row >> 1) & 7)) << 4); }
; #define MFMA32(a, b, c) __builtin_amdgcn_mfma_f32_32x32x16_bf16((a), (b), (c), 0, 0, 0)
;     ...
;         for (int kt = 0; kt < nk; ++kt) {
; #pragma unroll
;             for (int i = 0; i < 4; ++i) *(u32x4*)(lds + swz(lr + 32 * i, lc)) = ra[i];
; #pragma unroll
;             for (int i = 0; i < 8; ++i) *(u32x4*)(lds + 16384 + swz(lr + 32 * i, lc)) = rb[i];
;             __syncthreads();
;             if (kt + 1 < nk) {
; #pragma unroll
;                 for (int i = 0; i < 4; ++i) ra[i] = *(const u32x4*)((Au + (size_t)(32 * i) * lda + (kt + 1) * 64) + voA);
; #pragma unroll
;                 for (int i = 0; i < 8; ++i) rb[i] = *(const u32x4*)((Bu + (size_t)(32 * i) * ldb + (kt + 1) * 64) + voB);
;             }
;             __builtin_amdgcn_s_setprio(1);
; #pragma unroll 2
;             for (int ks = 0; ks < 4; ++ks) {
;                 bf16x8 af[2], bfr[4];
;                 const unsigned xo = (c0 ^ (unsigned)(2 * ks)) << 4;
; #pragma unroll
;                 for (int i = 0; i < 2; ++i) af[i] = *(const bf16x8*)(lds + (roA + xo) + i * 4096);
; #pragma unroll
;                 for (int j = 0; j < 4; ++j) bfr[j] = *(const bf16x8*)(lds + (roB + xo) + j * 4096);
; #pragma unroll
;                 for (int i = 0; i < 2; ++i)
; #pragma unroll
;                     for (int j = 0; j < 4; ++j) acc[i][j] = MFMA32(af[i], bfr[j], acc[i][j]);
;             }
;             __builtin_amdgcn_s_setprio(0);
;             __syncthreads();
.LBB0_141:
	s_mov_b32 s7, s5
	s_add_i32 s5, s5, 1
	s_cmp_lg_u32 s7, 15
	s_waitcnt vmcnt(9)
	ds_write_b128 v192, v[134:137]
	ds_write_b128 v192, v[130:133] offset:4096
	ds_write_b128 v192, v[138:141] offset:8192
	s_waitcnt vmcnt(7)
	ds_write_b128 v192, v[142:145] offset:12288
	ds_write_b128 v192, v[146:149] offset:16384
	s_waitcnt vmcnt(6)
	ds_write_b128 v192, v[150:153] offset:20480
	s_waitcnt vmcnt(5)
	ds_write_b128 v192, v[154:157] offset:24576
	s_waitcnt vmcnt(4)
	ds_write_b128 v192, v[158:161] offset:28672
	s_waitcnt vmcnt(3)
	ds_write_b128 v192, v[162:165] offset:32768
	s_waitcnt vmcnt(2)
	ds_write_b128 v192, v[166:169] offset:36864
	s_waitcnt vmcnt(1)
	ds_write_b128 v192, v[170:173] offset:40960
	s_waitcnt vmcnt(0)
	ds_write_b128 v192, v[174:177] offset:45056
	s_waitcnt lgkmcnt(0)
	s_barrier
	s_cbranch_scc0 .LBB0_143
	s_lshl_b32 s22, s5, 7
	s_mov_b32 s23, 0
	s_setprio 1
	v_xor_b32_e32 v0, 0, v187
	v_add_u32_e32 v195, v188, v0
	v_add_u32_e32 v0, v189, v0
	ds_read_b128 v[196:199], v195
	ds_read_b128 v[200:203], v0 offset:16384
	ds_read_b128 v[204:207], v195 offset:4096
	ds_read_b128 v[208:211], v0 offset:20480
	ds_read_b128 v[212:215], v0 offset:24576
	ds_read_b128 v[218:221], v0 offset:28672
	s_waitcnt lgkmcnt(4)
	v_mfma_f32_32x32x16_bf16 v[114:129], v[196:199], v[200:203], v[114:129]
	v_lshl_add_u64 v[222:223], v[182:183], 0, s[22:23]
	global_load_dwordx4 v[134:137], v[222:223], off
	s_add_u32 s22, s22, 0x10000
	s_mov_b32 s8, 32
	v_xor_b32_e32 v0, s8, v187
	v_add_u32_e32 v195, v188, v0
	v_add_u32_e32 v0, v189, v0
	s_waitcnt lgkmcnt(2)
	v_mfma_f32_32x32x16_bf16 v[82:97], v[196:199], v[208:211], v[82:97]
	s_waitcnt lgkmcnt(1)
	v_mfma_f32_32x32x16_bf16 v[98:113], v[196:199], v[212:215], v[98:113]
	v_lshl_add_u64 v[224:225], v[182:183], 0, s[22:23]
	global_load_dwordx4 v[130:133], v[224:225], off
	s_add_u32 s22, s22, 0x10000
	s_waitcnt lgkmcnt(0)
	v_mfma_f32_32x32x16_bf16 v[66:81], v[196:199], v[218:221], v[66:81]
	v_mfma_f32_32x32x16_bf16 v[50:65], v[204:207], v[200:203], v[50:65]
	v_lshl_add_u64 v[226:227], v[182:183], 0, s[22:23]
	global_load_dwordx4 v[138:141], v[226:227], off
	s_add_u32 s22, s22, 0x10000
	v_mfma_f32_32x32x16_bf16 v[34:49], v[204:207], v[208:211], v[34:49]
	v_mfma_f32_32x32x16_bf16 v[18:33], v[204:207], v[212:215], v[18:33]
	v_lshl_add_u64 v[222:223], v[182:183], 0, s[22:23]
	global_load_dwordx4 v[142:145], v[222:223], off
	s_sub_u32 s22, s22, 0x30000
	v_mfma_f32_32x32x16_bf16 v[2:17], v[204:207], v[218:221], v[2:17]
	ds_read_b128 v[196:199], v195
	ds_read_b128 v[200:203], v0 offset:16384
	ds_read_b128 v[204:207], v195 offset:4096
	ds_read_b128 v[208:211], v0 offset:20480
	ds_read_b128 v[212:215], v0 offset:24576
	ds_read_b128 v[218:221], v0 offset:28672
	s_waitcnt lgkmcnt(4)
	v_mfma_f32_32x32x16_bf16 v[114:129], v[196:199], v[200:203], v[114:129]
	v_lshl_add_u64 v[224:225], v[184:185], 0, s[22:23]
	global_load_dwordx4 v[146:149], v[224:225], off
	s_add_u32 s22, s22, 0x10000
	s_waitcnt lgkmcnt(2)
	v_mfma_f32_32x32x16_bf16 v[82:97], v[196:199], v[208:211], v[82:97]
	s_waitcnt lgkmcnt(1)
	v_mfma_f32_32x32x16_bf16 v[98:113], v[196:199], v[212:215], v[98:113]
	v_lshl_add_u64 v[226:227], v[184:185], 0, s[22:23]
	global_load_dwordx4 v[150:153], v[226:227], off
	s_add_u32 s22, s22, 0x10000
	s_waitcnt lgkmcnt(0)
	v_mfma_f32_32x32x16_bf16 v[66:81], v[196:199], v[218:221], v[66:81]
	v_mfma_f32_32x32x16_bf16 v[50:65], v[204:207], v[200:203], v[50:65]
	v_lshl_add_u64 v[222:223], v[184:185], 0, s[22:23]
	global_load_dwordx4 v[154:157], v[222:223], off
	s_add_u32 s22, s22, 0x10000
	v_mfma_f32_32x32x16_bf16 v[34:49], v[204:207], v[208:211], v[34:49]
	v_mfma_f32_32x32x16_bf16 v[18:33], v[204:207], v[212:215], v[18:33]
	v_lshl_add_u64 v[224:225], v[184:185], 0, s[22:23]
	global_load_dwordx4 v[158:161], v[224:225], off
	s_add_u32 s22, s22, 0x10000
	v_mfma_f32_32x32x16_bf16 v[2:17], v[204:207], v[218:221], v[2:17]
	v_xor_b32_e32 v0, 64, v187
	v_add_u32_e32 v195, v188, v0
	v_add_u32_e32 v0, v189, v0
	ds_read_b128 v[196:199], v195
	ds_read_b128 v[200:203], v0 offset:16384
	ds_read_b128 v[204:207], v195 offset:4096
	ds_read_b128 v[208:211], v0 offset:20480
	ds_read_b128 v[212:215], v0 offset:24576
	ds_read_b128 v[218:221], v0 offset:28672
	s_waitcnt lgkmcnt(4)
	v_mfma_f32_32x32x16_bf16 v[114:129], v[196:199], v[200:203], v[114:129]
	v_lshl_add_u64 v[226:227], v[184:185], 0, s[22:23]
	global_load_dwordx4 v[162:165], v[226:227], off
	s_add_u32 s22, s22, 0x10000
	s_mov_b32 s8, 96
	v_xor_b32_e32 v0, s8, v187
	v_add_u32_e32 v195, v188, v0
	v_add_u32_e32 v0, v189, v0
	s_waitcnt lgkmcnt(2)
	v_mfma_f32_32x32x16_bf16 v[82:97], v[196:199], v[208:211], v[82:97]
	s_waitcnt lgkmcnt(1)
	v_mfma_f32_32x32x16_bf16 v[98:113], v[196:199], v[212:215], v[98:113]
	v_lshl_add_u64 v[222:223], v[184:185], 0, s[22:23]
	global_load_dwordx4 v[166:169], v[222:223], off
	s_add_u32 s22, s22, 0x10000
	s_waitcnt lgkmcnt(0)
	v_mfma_f32_32x32x16_bf16 v[66:81], v[196:199], v[218:221], v[66:81]
	v_mfma_f32_32x32x16_bf16 v[50:65], v[204:207], v[200:203], v[50:65]
	v_lshl_add_u64 v[224:225], v[184:185], 0, s[22:23]
	global_load_dwordx4 v[170:173], v[224:225], off
	s_add_u32 s22, s22, 0x10000
	v_mfma_f32_32x32x16_bf16 v[34:49], v[204:207], v[208:211], v[34:49]
	v_mfma_f32_32x32x16_bf16 v[18:33], v[204:207], v[212:215], v[18:33]
	v_lshl_add_u64 v[226:227], v[184:185], 0, s[22:23]
	global_load_dwordx4 v[174:177], v[226:227], off
	v_mfma_f32_32x32x16_bf16 v[2:17], v[204:207], v[218:221], v[2:17]
	ds_read_b128 v[196:199], v195
	ds_read_b128 v[200:203], v0 offset:16384
	ds_read_b128 v[204:207], v195 offset:4096
	ds_read_b128 v[208:211], v0 offset:20480
	ds_read_b128 v[212:215], v0 offset:24576
	ds_read_b128 v[218:221], v0 offset:28672
	s_waitcnt lgkmcnt(4)
	v_mfma_f32_32x32x16_bf16 v[114:129], v[196:199], v[200:203], v[114:129]
	s_waitcnt lgkmcnt(2)
	v_mfma_f32_32x32x16_bf16 v[82:97], v[196:199], v[208:211], v[82:97]
	s_waitcnt lgkmcnt(1)
	v_mfma_f32_32x32x16_bf16 v[98:113], v[196:199], v[212:215], v[98:113]
	s_waitcnt lgkmcnt(0)
	v_mfma_f32_32x32x16_bf16 v[66:81], v[196:199], v[218:221], v[66:81]
	v_mfma_f32_32x32x16_bf16 v[50:65], v[204:207], v[200:203], v[50:65]
	v_mfma_f32_32x32x16_bf16 v[34:49], v[204:207], v[208:211], v[34:49]
	v_mfma_f32_32x32x16_bf16 v[18:33], v[204:207], v[212:215], v[18:33]
	v_mfma_f32_32x32x16_bf16 v[2:17], v[204:207], v[218:221], v[2:17]
	s_branch .Lkint_done_144

; DI unsigned swz(int row, int chunk) { return (unsigned)row * 128u + (unsigned)((chunk ^ ((row >> 1) & 7)) << 4); }
; #define MFMA32(a, b, c) __builtin_amdgcn_mfma_f32_32x32x16_bf16((a), (b), (c), 0, 0, 0)
;     ...
;         for (int kt = 0; kt < nk; ++kt) {
; #pragma unroll
;             for (int i = 0; i < 4; ++i) *(u32x4*)(lds + swz(lr + 32 * i, lc)) = ra[i];
; #pragma unroll
;             for (int i = 0; i < 8; ++i) *(u32x4*)(lds + 16384 + swz(lr + 32 * i, lc)) = rb[i];
;             __syncthreads();
;             if (kt + 1 < nk) {
; #pragma unroll
;                 for (int i = 0; i < 4; ++i) ra[i] = *(const u32x4*)((Au + (size_t)(32 * i) * lda + (kt + 1) * 64) + voA);
; #pragma unroll
;                 for (int i = 0; i < 8; ++i) rb[i] = *(const u32x4*)((Bu + (size_t)(32 * i) * ldb + (kt + 1) * 64) + voB);
;             }
;             __builtin_amdgcn_s_setprio(1);
; #pragma unroll 2
;             for (int ks = 0; ks < 4; ++ks) {
;                 bf16x8 af[2], bfr[4];
;                 const unsigned xo = (c0 ^ (unsigned)(2 * ks)) << 4;
; #pragma unroll
;                 for (int i = 0; i < 2; ++i) af[i] = *(const bf16x8*)(lds + (roA + xo) + i * 4096);
; #pragma unroll
;                 for (int j = 0; j < 4; ++j) bfr[j] = *(const bf16x8*)(lds + (roB + xo) + j * 4096);
; #pragma unroll
;                 for (int i = 0; i < 2; ++i)
; #pragma unroll
;                     for (int j = 0; j < 4; ++j) acc[i][j] = MFMA32(af[i], bfr[j], acc[i][j]);
;             }
;             __builtin_amdgcn_s_setprio(0);
;             __syncthreads();
.LBB0_644:
	s_mov_b32 s4, s7
	s_add_i32 s7, s7, 1
	s_cmp_lt_u32 s4, 15
	s_waitcnt vmcnt(0)
	ds_write_b128 v224, v[130:133]
	ds_write_b128 v224, v[138:141] offset:4096
	ds_write_b128 v224, v[170:173] offset:8192
	ds_write_b128 v224, v[134:137] offset:12288
	ds_write_b128 v224, v[174:177] offset:16384
	ds_write_b128 v224, v[166:169] offset:20480
	ds_write_b128 v224, v[162:165] offset:24576
	ds_write_b128 v224, v[158:161] offset:28672
	ds_write_b128 v224, v[154:157] offset:32768
	ds_write_b128 v224, v[150:153] offset:36864
	ds_write_b128 v224, v[146:149] offset:40960
	ds_write_b128 v224, v[142:145] offset:45056
	s_waitcnt lgkmcnt(0)
	s_barrier
	s_cbranch_scc0 .LBB0_646
	s_lshl_b32 s10, s7, 7
	s_mov_b32 s11, 0
	s_setprio 1
	v_xor_b32_e32 v1, 0, v219
	v_add_u32_e32 v206, v220, v1
	v_add_u32_e32 v1, v221, v1
	ds_read_b128 v[186:189], v206
	ds_read_b128 v[190:193], v1 offset:16384
	ds_read_b128 v[194:197], v1 offset:20480
	ds_read_b128 v[198:201], v1 offset:24576
	ds_read_b128 v[202:205], v1 offset:28672
	s_waitcnt lgkmcnt(3)
	v_mfma_f32_32x32x16_bf16 v[114:129], v[186:189], v[190:193], v[114:129]
	v_lshl_add_u64 v[226:227], v[182:183], 0, s[10:11]
	global_load_dwordx4 v[130:133], v[226:227], off
	s_add_u32 s10, s10, 0x10000
	s_mov_b32 s9, 32
	v_xor_b32_e32 v1, s9, v219
	s_waitcnt lgkmcnt(2)
	v_mfma_f32_32x32x16_bf16 v[82:97], v[186:189], v[194:197], v[82:97]
	s_waitcnt lgkmcnt(1)
	v_mfma_f32_32x32x16_bf16 v[50:65], v[186:189], v[198:201], v[50:65]
	v_lshl_add_u64 v[228:229], v[182:183], 0, s[10:11]
	global_load_dwordx4 v[138:141], v[228:229], off
	s_add_u32 s10, s10, 0x10000
	s_waitcnt lgkmcnt(0)
	v_mfma_f32_32x32x16_bf16 v[18:33], v[186:189], v[202:205], v[18:33]
	ds_read_b128 v[186:189], v206 offset:4096
	v_add_u32_e32 v206, v220, v1
	v_add_u32_e32 v1, v221, v1
	s_waitcnt lgkmcnt(0)
	v_mfma_f32_32x32x16_bf16 v[98:113], v[186:189], v[190:193], v[98:113]
	v_lshl_add_u64 v[230:231], v[182:183], 0, s[10:11]
	global_load_dwordx4 v[170:173], v[230:231], off
	s_add_u32 s10, s10, 0x10000
	v_mfma_f32_32x32x16_bf16 v[66:81], v[186:189], v[194:197], v[66:81]
	v_mfma_f32_32x32x16_bf16 v[34:49], v[186:189], v[198:201], v[34:49]
	v_lshl_add_u64 v[226:227], v[182:183], 0, s[10:11]
	global_load_dwordx4 v[134:137], v[226:227], off
	s_sub_u32 s10, s10, 0x30000
	v_mfma_f32_32x32x16_bf16 v[2:17], v[186:189], v[202:205], v[2:17]
	ds_read_b128 v[186:189], v206
	ds_read_b128 v[190:193], v1 offset:16384
	ds_read_b128 v[194:197], v1 offset:20480
	ds_read_b128 v[198:201], v1 offset:24576
	ds_read_b128 v[202:205], v1 offset:28672
	s_waitcnt lgkmcnt(3)
	v_mfma_f32_32x32x16_bf16 v[114:129], v[186:189], v[190:193], v[114:129]
	v_lshl_add_u64 v[228:229], v[184:185], 0, s[10:11]
	global_load_dwordx4 v[174:177], v[228:229], off
	s_add_u32 s10, s10, 0x10000
	s_waitcnt lgkmcnt(2)
	v_mfma_f32_32x32x16_bf16 v[82:97], v[186:189], v[194:197], v[82:97]
	s_waitcnt lgkmcnt(1)
	v_mfma_f32_32x32x16_bf16 v[50:65], v[186:189], v[198:201], v[50:65]
	v_lshl_add_u64 v[230:231], v[184:185], 0, s[10:11]
	global_load_dwordx4 v[166:169], v[230:231], off
	s_add_u32 s10, s10, 0x10000
	s_waitcnt lgkmcnt(0)
	v_mfma_f32_32x32x16_bf16 v[18:33], v[186:189], v[202:205], v[18:33]
	ds_read_b128 v[186:189], v206 offset:4096
	s_waitcnt lgkmcnt(0)
	v_mfma_f32_32x32x16_bf16 v[98:113], v[186:189], v[190:193], v[98:113]
	v_lshl_add_u64 v[226:227], v[184:185], 0, s[10:11]
	global_load_dwordx4 v[162:165], v[226:227], off
	s_add_u32 s10, s10, 0x10000
	v_mfma_f32_32x32x16_bf16 v[66:81], v[186:189], v[194:197], v[66:81]
	v_mfma_f32_32x32x16_bf16 v[34:49], v[186:189], v[198:201], v[34:49]
	v_lshl_add_u64 v[228:229], v[184:185], 0, s[10:11]
	global_load_dwordx4 v[158:161], v[228:229], off
	s_add_u32 s10, s10, 0x10000
	v_mfma_f32_32x32x16_bf16 v[2:17], v[186:189], v[202:205], v[2:17]
	v_xor_b32_e32 v1, 64, v219
	v_add_u32_e32 v206, v220, v1
	v_add_u32_e32 v1, v221, v1
	ds_read_b128 v[186:189], v206
	ds_read_b128 v[190:193], v1 offset:16384
	ds_read_b128 v[194:197], v1 offset:20480
	ds_read_b128 v[198:201], v1 offset:24576
	ds_read_b128 v[202:205], v1 offset:28672
	s_waitcnt lgkmcnt(3)
	v_mfma_f32_32x32x16_bf16 v[114:129], v[186:189], v[190:193], v[114:129]
	v_lshl_add_u64 v[230:231], v[184:185], 0, s[10:11]
	global_load_dwordx4 v[154:157], v[230:231], off
	s_add_u32 s10, s10, 0x10000
	s_mov_b32 s9, 96
	v_xor_b32_e32 v1, s9, v219
	s_waitcnt lgkmcnt(2)
	v_mfma_f32_32x32x16_bf16 v[82:97], v[186:189], v[194:197], v[82:97]
	s_waitcnt lgkmcnt(1)
	v_mfma_f32_32x32x16_bf16 v[50:65], v[186:189], v[198:201], v[50:65]
	v_lshl_add_u64 v[226:227], v[184:185], 0, s[10:11]
	global_load_dwordx4 v[150:153], v[226:227], off
	s_add_u32 s10, s10, 0x10000
	s_waitcnt lgkmcnt(0)
	v_mfma_f32_32x32x16_bf16 v[18:33], v[186:189], v[202:205], v[18:33]
	ds_read_b128 v[186:189], v206 offset:4096
	v_add_u32_e32 v206, v220, v1
	v_add_u32_e32 v1, v221, v1
	s_waitcnt lgkmcnt(0)
	v_mfma_f32_32x32x16_bf16 v[98:113], v[186:189], v[190:193], v[98:113]
	v_lshl_add_u64 v[228:229], v[184:185], 0, s[10:11]
	global_load_dwordx4 v[146:149], v[228:229], off
	s_add_u32 s10, s10, 0x10000
	v_mfma_f32_32x32x16_bf16 v[66:81], v[186:189], v[194:197], v[66:81]
	v_mfma_f32_32x32x16_bf16 v[34:49], v[186:189], v[198:201], v[34:49]
	v_lshl_add_u64 v[230:231], v[184:185], 0, s[10:11]
	global_load_dwordx4 v[142:145], v[230:231], off
	v_mfma_f32_32x32x16_bf16 v[2:17], v[186:189], v[202:205], v[2:17]
	ds_read_b128 v[186:189], v206
	ds_read_b128 v[190:193], v1 offset:16384
	ds_read_b128 v[194:197], v1 offset:20480
	ds_read_b128 v[198:201], v1 offset:24576
	ds_read_b128 v[202:205], v1 offset:28672
	s_waitcnt lgkmcnt(3)
	v_mfma_f32_32x32x16_bf16 v[114:129], v[186:189], v[190:193], v[114:129]
	s_waitcnt lgkmcnt(2)
	v_mfma_f32_32x32x16_bf16 v[82:97], v[186:189], v[194:197], v[82:97]
	s_waitcnt lgkmcnt(1)
	v_mfma_f32_32x32x16_bf16 v[50:65], v[186:189], v[198:201], v[50:65]
	s_waitcnt lgkmcnt(0)
	v_mfma_f32_32x32x16_bf16 v[18:33], v[186:189], v[202:205], v[18:33]
	ds_read_b128 v[186:189], v206 offset:4096
	s_waitcnt lgkmcnt(0)
	v_mfma_f32_32x32x16_bf16 v[98:113], v[186:189], v[190:193], v[98:113]
	v_mfma_f32_32x32x16_bf16 v[66:81], v[186:189], v[194:197], v[66:81]
	v_mfma_f32_32x32x16_bf16 v[34:49], v[186:189], v[198:201], v[34:49]
	v_mfma_f32_32x32x16_bf16 v[2:17], v[186:189], v[202:205], v[2:17]
	s_branch .Lkint_done_647

; DI unsigned swz(int row, int chunk) { return (unsigned)row * 128u + (unsigned)((chunk ^ ((row >> 1) & 7)) << 4); }
; #define MFMA32(a, b, c) __builtin_amdgcn_mfma_f32_32x32x16_bf16((a), (b), (c), 0, 0, 0)
;     ...
;         for (int kt = 0; kt < nk; ++kt) {
; #pragma unroll
;             for (int i = 0; i < 4; ++i) *(u32x4*)(lds + swz(lr + 32 * i, lc)) = ra[i];
; #pragma unroll
;             for (int i = 0; i < 8; ++i) *(u32x4*)(lds + 16384 + swz(lr + 32 * i, lc)) = rb[i];
;             __syncthreads();
;             if (kt + 1 < nk) {
; #pragma unroll
;                 for (int i = 0; i < 4; ++i) ra[i] = *(const u32x4*)((Au + (size_t)(32 * i) * lda + (kt + 1) * 64) + voA);
; #pragma unroll
;                 for (int i = 0; i < 8; ++i) rb[i] = *(const u32x4*)((Bu + (size_t)(32 * i) * ldb + (kt + 1) * 64) + voB);
;             }
;             __builtin_amdgcn_s_setprio(1);
; #pragma unroll 2
;             for (int ks = 0; ks < 4; ++ks) {
;                 bf16x8 af[2], bfr[4];
;                 const unsigned xo = (c0 ^ (unsigned)(2 * ks)) << 4;
; #pragma unroll
;                 for (int i = 0; i < 2; ++i) af[i] = *(const bf16x8*)(lds + (roA + xo) + i * 4096);
; #pragma unroll
;                 for (int j = 0; j < 4; ++j) bfr[j] = *(const bf16x8*)(lds + (roB + xo) + j * 4096);
; #pragma unroll
;                 for (int i = 0; i < 2; ++i)
; #pragma unroll
;                     for (int j = 0; j < 4; ++j) acc[i][j] = MFMA32(af[i], bfr[j], acc[i][j]);
;             }
;             __builtin_amdgcn_s_setprio(0);
;             __syncthreads();
.LBB0_734:
	s_mov_b32 s4, s7
	s_add_i32 s7, s7, 1
	s_cmp_lg_u32 s4, 15
	s_waitcnt vmcnt(9)
	ds_write_b128 v206, v[148:151]
	ds_write_b128 v206, v[144:147] offset:4096
	ds_write_b128 v206, v[152:155] offset:8192
	s_waitcnt vmcnt(7)
	ds_write_b128 v206, v[156:159] offset:12288
	ds_write_b128 v206, v[160:163] offset:16384
	s_waitcnt vmcnt(6)
	ds_write_b128 v206, v[164:167] offset:20480
	s_waitcnt vmcnt(5)
	ds_write_b128 v206, v[168:171] offset:24576
	s_waitcnt vmcnt(4)
	ds_write_b128 v206, v[172:175] offset:28672
	s_waitcnt vmcnt(3)
	ds_write_b128 v206, v[176:179] offset:32768
	s_waitcnt vmcnt(2)
	ds_write_b128 v206, v[180:183] offset:36864
	s_waitcnt vmcnt(1)
	ds_write_b128 v206, v[184:187] offset:40960
	s_waitcnt vmcnt(0)
	ds_write_b128 v206, v[188:191] offset:45056
	s_waitcnt lgkmcnt(0)
	s_barrier
	s_cbranch_scc0 .LBB0_736
	s_lshl_b32 s10, s7, 7
	s_mov_b32 s11, 0
	s_setprio 1
	v_xor_b32_e32 v1, 0, v201
	v_add_u32_e32 v10, v202, v1
	v_add_u32_e32 v1, v203, v1
	ds_read_b128 v[2:5], v10
	ds_read_b128 v[6:9], v1 offset:16384
	ds_read_b128 v[10:13], v10 offset:4096
	ds_read_b128 v[208:211], v1 offset:20480
	ds_read_b128 v[212:215], v1 offset:24576
	ds_read_b128 v[218:221], v1 offset:28672
	s_waitcnt lgkmcnt(4)
	v_mfma_f32_32x32x16_bf16 v[128:143], v[2:5], v[6:9], v[128:143]
	v_lshl_add_u64 v[222:223], v[196:197], 0, s[10:11]
	global_load_dwordx4 v[148:151], v[222:223], off
	s_add_u32 s10, s10, 0x10000
	s_mov_b32 s9, 32
	v_xor_b32_e32 v1, s9, v201
	v_add_u32_e32 v14, v202, v1
	v_add_u32_e32 v1, v203, v1
	s_waitcnt lgkmcnt(2)
	v_mfma_f32_32x32x16_bf16 v[112:127], v[2:5], v[208:211], v[112:127]
	s_waitcnt lgkmcnt(1)
	v_mfma_f32_32x32x16_bf16 v[48:63], v[2:5], v[212:215], v[48:63]
	v_lshl_add_u64 v[224:225], v[196:197], 0, s[10:11]
	global_load_dwordx4 v[144:147], v[224:225], off
	s_add_u32 s10, s10, 0x10000
	s_waitcnt lgkmcnt(0)
	v_mfma_f32_32x32x16_bf16 v[64:79], v[2:5], v[218:221], v[64:79]
	v_mfma_f32_32x32x16_bf16 v[80:95], v[10:13], v[6:9], v[80:95]
	v_lshl_add_u64 v[226:227], v[196:197], 0, s[10:11]
	global_load_dwordx4 v[152:155], v[226:227], off
	s_add_u32 s10, s10, 0x10000
	v_mfma_f32_32x32x16_bf16 v[96:111], v[10:13], v[208:211], v[96:111]
	v_mfma_f32_32x32x16_bf16 v[16:31], v[10:13], v[212:215], v[16:31]
	v_lshl_add_u64 v[222:223], v[196:197], 0, s[10:11]
	global_load_dwordx4 v[156:159], v[222:223], off
	s_sub_u32 s10, s10, 0x30000
	v_mfma_f32_32x32x16_bf16 v[32:47], v[10:13], v[218:221], v[32:47]
	ds_read_b128 v[2:5], v14
	ds_read_b128 v[6:9], v1 offset:16384
	ds_read_b128 v[10:13], v14 offset:4096
	ds_read_b128 v[208:211], v1 offset:20480
	ds_read_b128 v[212:215], v1 offset:24576
	ds_read_b128 v[218:221], v1 offset:28672
	s_waitcnt lgkmcnt(4)
	v_mfma_f32_32x32x16_bf16 v[128:143], v[2:5], v[6:9], v[128:143]
	v_lshl_add_u64 v[224:225], v[198:199], 0, s[10:11]
	global_load_dwordx4 v[160:163], v[224:225], off
	s_add_u32 s10, s10, 0x10000
	s_waitcnt lgkmcnt(2)
	v_mfma_f32_32x32x16_bf16 v[112:127], v[2:5], v[208:211], v[112:127]
	s_waitcnt lgkmcnt(1)
	v_mfma_f32_32x32x16_bf16 v[48:63], v[2:5], v[212:215], v[48:63]
	v_lshl_add_u64 v[226:227], v[198:199], 0, s[10:11]
	global_load_dwordx4 v[164:167], v[226:227], off
	s_add_u32 s10, s10, 0x10000
	s_waitcnt lgkmcnt(0)
	v_mfma_f32_32x32x16_bf16 v[64:79], v[2:5], v[218:221], v[64:79]
	v_mfma_f32_32x32x16_bf16 v[80:95], v[10:13], v[6:9], v[80:95]
	v_lshl_add_u64 v[222:223], v[198:199], 0, s[10:11]
	global_load_dwordx4 v[168:171], v[222:223], off
	s_add_u32 s10, s10, 0x10000
	v_mfma_f32_32x32x16_bf16 v[96:111], v[10:13], v[208:211], v[96:111]
	v_mfma_f32_32x32x16_bf16 v[16:31], v[10:13], v[212:215], v[16:31]
	v_lshl_add_u64 v[224:225], v[198:199], 0, s[10:11]
	global_load_dwordx4 v[172:175], v[224:225], off
	s_add_u32 s10, s10, 0x10000
	v_mfma_f32_32x32x16_bf16 v[32:47], v[10:13], v[218:221], v[32:47]
	v_xor_b32_e32 v1, 64, v201
	v_add_u32_e32 v10, v202, v1
	v_add_u32_e32 v1, v203, v1
	ds_read_b128 v[2:5], v10
	ds_read_b128 v[6:9], v1 offset:16384
	ds_read_b128 v[10:13], v10 offset:4096
	ds_read_b128 v[208:211], v1 offset:20480
	ds_read_b128 v[212:215], v1 offset:24576
	ds_read_b128 v[218:221], v1 offset:28672
	s_waitcnt lgkmcnt(4)
	v_mfma_f32_32x32x16_bf16 v[128:143], v[2:5], v[6:9], v[128:143]
	v_lshl_add_u64 v[226:227], v[198:199], 0, s[10:11]
	global_load_dwordx4 v[176:179], v[226:227], off
	s_add_u32 s10, s10, 0x10000
	s_mov_b32 s9, 96
	v_xor_b32_e32 v1, s9, v201
	v_add_u32_e32 v14, v202, v1
	v_add_u32_e32 v1, v203, v1
	s_waitcnt lgkmcnt(2)
	v_mfma_f32_32x32x16_bf16 v[112:127], v[2:5], v[208:211], v[112:127]
	s_waitcnt lgkmcnt(1)
	v_mfma_f32_32x32x16_bf16 v[48:63], v[2:5], v[212:215], v[48:63]
	v_lshl_add_u64 v[222:223], v[198:199], 0, s[10:11]
	global_load_dwordx4 v[180:183], v[222:223], off
	s_add_u32 s10, s10, 0x10000
	s_waitcnt lgkmcnt(0)
	v_mfma_f32_32x32x16_bf16 v[64:79], v[2:5], v[218:221], v[64:79]
	v_mfma_f32_32x32x16_bf16 v[80:95], v[10:13], v[6:9], v[80:95]
	v_lshl_add_u64 v[224:225], v[198:199], 0, s[10:11]
	global_load_dwordx4 v[184:187], v[224:225], off
	s_add_u32 s10, s10, 0x10000
	v_mfma_f32_32x32x16_bf16 v[96:111], v[10:13], v[208:211], v[96:111]
	v_mfma_f32_32x32x16_bf16 v[16:31], v[10:13], v[212:215], v[16:31]
	v_lshl_add_u64 v[226:227], v[198:199], 0, s[10:11]
	global_load_dwordx4 v[188:191], v[226:227], off
	v_mfma_f32_32x32x16_bf16 v[32:47], v[10:13], v[218:221], v[32:47]
	ds_read_b128 v[2:5], v14
	ds_read_b128 v[6:9], v1 offset:16384
	ds_read_b128 v[10:13], v14 offset:4096
	ds_read_b128 v[208:211], v1 offset:20480
	ds_read_b128 v[212:215], v1 offset:24576
	ds_read_b128 v[218:221], v1 offset:28672
	s_waitcnt lgkmcnt(4)
	v_mfma_f32_32x32x16_bf16 v[128:143], v[2:5], v[6:9], v[128:143]
	s_waitcnt lgkmcnt(2)
	v_mfma_f32_32x32x16_bf16 v[112:127], v[2:5], v[208:211], v[112:127]
	s_waitcnt lgkmcnt(1)
	v_mfma_f32_32x32x16_bf16 v[48:63], v[2:5], v[212:215], v[48:63]
	s_waitcnt lgkmcnt(0)
	v_mfma_f32_32x32x16_bf16 v[64:79], v[2:5], v[218:221], v[64:79]
	v_mfma_f32_32x32x16_bf16 v[80:95], v[10:13], v[6:9], v[80:95]
	v_mfma_f32_32x32x16_bf16 v[96:111], v[10:13], v[208:211], v[96:111]
	v_mfma_f32_32x32x16_bf16 v[16:31], v[10:13], v[212:215], v[16:31]
	v_mfma_f32_32x32x16_bf16 v[32:47], v[10:13], v[218:221], v[32:47]
	s_branch .Lkint_done_737

; DI unsigned swz(int row, int chunk) { return (unsigned)row * 128u + (unsigned)((chunk ^ ((row >> 1) & 7)) << 4); }
; #define MFMA32(a, b, c) __builtin_amdgcn_mfma_f32_32x32x16_bf16((a), (b), (c), 0, 0, 0)
;     ...
;         for (int kt = 0; kt < nk; ++kt) {
; #pragma unroll
;             for (int i = 0; i < 4; ++i) *(u32x4*)(lds + swz(lr + 32 * i, lc)) = ra[i];
; #pragma unroll
;             for (int i = 0; i < 8; ++i) *(u32x4*)(lds + 16384 + swz(lr + 32 * i, lc)) = rb[i];
;             __syncthreads();
;             if (kt + 1 < nk) {
; #pragma unroll
;                 for (int i = 0; i < 4; ++i) ra[i] = *(const u32x4*)((Au + (size_t)(32 * i) * lda + (kt + 1) * 64) + voA);
; #pragma unroll
;                 for (int i = 0; i < 8; ++i) rb[i] = *(const u32x4*)((Bu + (size_t)(32 * i) * ldb + (kt + 1) * 64) + voB);
;             }
;             __builtin_amdgcn_s_setprio(1);
; #pragma unroll 2
;             for (int ks = 0; ks < 4; ++ks) {
;                 bf16x8 af[2], bfr[4];
;                 const unsigned xo = (c0 ^ (unsigned)(2 * ks)) << 4;
; #pragma unroll
;                 for (int i = 0; i < 2; ++i) af[i] = *(const bf16x8*)(lds + (roA + xo) + i * 4096);
; #pragma unroll
;                 for (int j = 0; j < 4; ++j) bfr[j] = *(const bf16x8*)(lds + (roB + xo) + j * 4096);
; #pragma unroll
;                 for (int i = 0; i < 2; ++i)
; #pragma unroll
;                     for (int j = 0; j < 4; ++j) acc[i][j] = MFMA32(af[i], bfr[j], acc[i][j]);
;             }
;             __builtin_amdgcn_s_setprio(0);
;             __syncthreads();
.LBB0_780:
	s_mov_b32 s0, s94
	s_add_i32 s94, s94, 1
	s_cmp_lt_u32 s0, 43
	s_waitcnt vmcnt(0)
	ds_write_b128 v193, v[130:133]
	ds_write_b128 v193, v[138:141] offset:4096
	ds_write_b128 v193, v[170:173] offset:8192
	ds_write_b128 v193, v[134:137] offset:12288
	ds_write_b128 v193, v[174:177] offset:16384
	ds_write_b128 v193, v[166:169] offset:20480
	ds_write_b128 v193, v[162:165] offset:24576
	ds_write_b128 v193, v[158:161] offset:28672
	ds_write_b128 v193, v[154:157] offset:32768
	ds_write_b128 v193, v[150:153] offset:36864
	ds_write_b128 v193, v[146:149] offset:40960
	ds_write_b128 v193, v[142:145] offset:45056
	s_waitcnt lgkmcnt(0)
	s_barrier
	s_cbranch_scc0 .LBB0_782
	s_lshl_b32 s18, s94, 7
	s_mov_b32 s19, 0
	s_setprio 1
	v_xor_b32_e32 v1, 0, v187
	v_add_u32_e32 v202, v188, v1
	v_add_u32_e32 v1, v189, v1
	ds_read_b128 v[194:197], v202
	ds_read_b128 v[198:201], v1 offset:16384
	ds_read_b128 v[202:205], v202 offset:4096
	ds_read_b128 v[206:209], v1 offset:20480
	ds_read_b128 v[210:213], v1 offset:24576
	ds_read_b128 v[218:221], v1 offset:28672
	s_waitcnt lgkmcnt(4)
	v_mfma_f32_32x32x16_bf16 v[114:129], v[194:197], v[198:201], v[114:129]
	v_lshl_add_u64 v[222:223], v[182:183], 0, s[18:19]
	global_load_dwordx4 v[130:133], v[222:223], off
	s_add_u32 s18, s18, 0x2c000
	s_mov_b32 s10, 32
	v_xor_b32_e32 v1, s10, v187
	s_waitcnt lgkmcnt(2)
	v_mfma_f32_32x32x16_bf16 v[82:97], v[194:197], v[206:209], v[82:97]
	s_waitcnt lgkmcnt(1)
	v_mfma_f32_32x32x16_bf16 v[50:65], v[194:197], v[210:213], v[50:65]
	v_lshl_add_u64 v[224:225], v[182:183], 0, s[18:19]
	global_load_dwordx4 v[138:141], v[224:225], off
	s_add_u32 s18, s18, 0x2c000
	s_waitcnt lgkmcnt(0)
	v_mfma_f32_32x32x16_bf16 v[18:33], v[194:197], v[218:221], v[18:33]
	v_mfma_f32_32x32x16_bf16 v[98:113], v[202:205], v[198:201], v[98:113]
	v_lshl_add_u64 v[226:227], v[182:183], 0, s[18:19]
	global_load_dwordx4 v[170:173], v[226:227], off
	s_add_u32 s18, s18, 0x2c000
	v_mfma_f32_32x32x16_bf16 v[66:81], v[202:205], v[206:209], v[66:81]
	v_add_u32_e32 v206, v188, v1
	v_add_u32_e32 v1, v189, v1
	v_mfma_f32_32x32x16_bf16 v[34:49], v[202:205], v[210:213], v[34:49]
	v_lshl_add_u64 v[222:223], v[182:183], 0, s[18:19]
	global_load_dwordx4 v[134:137], v[222:223], off
	s_sub_u32 s18, s18, 0x84000
	v_mfma_f32_32x32x16_bf16 v[2:17], v[202:205], v[218:221], v[2:17]
	ds_read_b128 v[194:197], v206
	ds_read_b128 v[198:201], v1 offset:16384
	ds_read_b128 v[202:205], v206 offset:4096
	ds_read_b128 v[206:209], v1 offset:20480
	ds_read_b128 v[210:213], v1 offset:24576
	ds_read_b128 v[218:221], v1 offset:28672
	s_waitcnt lgkmcnt(4)
	v_mfma_f32_32x32x16_bf16 v[114:129], v[194:197], v[198:201], v[114:129]
	v_lshl_add_u64 v[224:225], v[184:185], 0, s[18:19]
	global_load_dwordx4 v[174:177], v[224:225], off
	s_add_u32 s18, s18, 0x2c000
	s_waitcnt lgkmcnt(2)
	v_mfma_f32_32x32x16_bf16 v[82:97], v[194:197], v[206:209], v[82:97]
	s_waitcnt lgkmcnt(1)
	v_mfma_f32_32x32x16_bf16 v[50:65], v[194:197], v[210:213], v[50:65]
	v_lshl_add_u64 v[226:227], v[184:185], 0, s[18:19]
	global_load_dwordx4 v[166:169], v[226:227], off
	s_add_u32 s18, s18, 0x2c000
	s_waitcnt lgkmcnt(0)
	v_mfma_f32_32x32x16_bf16 v[18:33], v[194:197], v[218:221], v[18:33]
	v_mfma_f32_32x32x16_bf16 v[98:113], v[202:205], v[198:201], v[98:113]
	v_lshl_add_u64 v[222:223], v[184:185], 0, s[18:19]
	global_load_dwordx4 v[162:165], v[222:223], off
	s_add_u32 s18, s18, 0x2c000
	v_mfma_f32_32x32x16_bf16 v[66:81], v[202:205], v[206:209], v[66:81]
	v_mfma_f32_32x32x16_bf16 v[34:49], v[202:205], v[210:213], v[34:49]
	v_lshl_add_u64 v[224:225], v[184:185], 0, s[18:19]
	global_load_dwordx4 v[158:161], v[224:225], off
	s_add_u32 s18, s18, 0x2c000
	v_mfma_f32_32x32x16_bf16 v[2:17], v[202:205], v[218:221], v[2:17]
	v_xor_b32_e32 v1, 64, v187
	v_add_u32_e32 v202, v188, v1
	v_add_u32_e32 v1, v189, v1
	ds_read_b128 v[194:197], v202
	ds_read_b128 v[198:201], v1 offset:16384
	ds_read_b128 v[202:205], v202 offset:4096
	ds_read_b128 v[206:209], v1 offset:20480
	ds_read_b128 v[210:213], v1 offset:24576
	ds_read_b128 v[218:221], v1 offset:28672
	s_waitcnt lgkmcnt(4)
	v_mfma_f32_32x32x16_bf16 v[114:129], v[194:197], v[198:201], v[114:129]
	v_lshl_add_u64 v[226:227], v[184:185], 0, s[18:19]
	global_load_dwordx4 v[154:157], v[226:227], off
	s_add_u32 s18, s18, 0x2c000
	s_mov_b32 s10, 96
	v_xor_b32_e32 v1, s10, v187
	s_waitcnt lgkmcnt(2)
	v_mfma_f32_32x32x16_bf16 v[82:97], v[194:197], v[206:209], v[82:97]
	s_waitcnt lgkmcnt(1)
	v_mfma_f32_32x32x16_bf16 v[50:65], v[194:197], v[210:213], v[50:65]
	v_lshl_add_u64 v[222:223], v[184:185], 0, s[18:19]
	global_load_dwordx4 v[150:153], v[222:223], off
	s_add_u32 s18, s18, 0x2c000
	s_waitcnt lgkmcnt(0)
	v_mfma_f32_32x32x16_bf16 v[18:33], v[194:197], v[218:221], v[18:33]
	v_mfma_f32_32x32x16_bf16 v[98:113], v[202:205], v[198:201], v[98:113]
	v_lshl_add_u64 v[224:225], v[184:185], 0, s[18:19]
	global_load_dwordx4 v[146:149], v[224:225], off
	s_add_u32 s18, s18, 0x2c000
	v_mfma_f32_32x32x16_bf16 v[66:81], v[202:205], v[206:209], v[66:81]
	v_add_u32_e32 v206, v188, v1
	v_add_u32_e32 v1, v189, v1
	v_mfma_f32_32x32x16_bf16 v[34:49], v[202:205], v[210:213], v[34:49]
	v_lshl_add_u64 v[226:227], v[184:185], 0, s[18:19]
	global_load_dwordx4 v[142:145], v[226:227], off
	v_mfma_f32_32x32x16_bf16 v[2:17], v[202:205], v[218:221], v[2:17]
	ds_read_b128 v[194:197], v206
	ds_read_b128 v[198:201], v1 offset:16384
	ds_read_b128 v[202:205], v206 offset:4096
	ds_read_b128 v[206:209], v1 offset:20480
	ds_read_b128 v[210:213], v1 offset:24576
	ds_read_b128 v[218:221], v1 offset:28672
	s_waitcnt lgkmcnt(4)
	v_mfma_f32_32x32x16_bf16 v[114:129], v[194:197], v[198:201], v[114:129]
	s_waitcnt lgkmcnt(2)
	v_mfma_f32_32x32x16_bf16 v[82:97], v[194:197], v[206:209], v[82:97]
	s_waitcnt lgkmcnt(1)
	v_mfma_f32_32x32x16_bf16 v[50:65], v[194:197], v[210:213], v[50:65]
	s_waitcnt lgkmcnt(0)
	v_mfma_f32_32x32x16_bf16 v[18:33], v[194:197], v[218:221], v[18:33]
	v_mfma_f32_32x32x16_bf16 v[98:113], v[202:205], v[198:201], v[98:113]
	v_mfma_f32_32x32x16_bf16 v[66:81], v[202:205], v[206:209], v[66:81]
	v_mfma_f32_32x32x16_bf16 v[34:49], v[202:205], v[210:213], v[34:49]
	v_mfma_f32_32x32x16_bf16 v[2:17], v[202:205], v[218:221], v[2:17]
	s_branch .Lkint_done_783

; DI unsigned swz(int row, int chunk) { return (unsigned)row * 128u + (unsigned)((chunk ^ ((row >> 1) & 7)) << 4); }
; #define MFMA32(a, b, c) __builtin_amdgcn_mfma_f32_32x32x16_bf16((a), (b), (c), 0, 0, 0)
;     ...
;         for (int kt = 0; kt < nk; ++kt) {
; #pragma unroll
;             for (int i = 0; i < 4; ++i) *(u32x4*)(lds + swz(lr + 32 * i, lc)) = ra[i];
; #pragma unroll
;             for (int i = 0; i < 8; ++i) *(u32x4*)(lds + 16384 + swz(lr + 32 * i, lc)) = rb[i];
;             __syncthreads();
;             if (kt + 1 < nk) {
; #pragma unroll
;                 for (int i = 0; i < 4; ++i) ra[i] = *(const u32x4*)((Au + (size_t)(32 * i) * lda + (kt + 1) * 64) + voA);
; #pragma unroll
;                 for (int i = 0; i < 8; ++i) rb[i] = *(const u32x4*)((Bu + (size_t)(32 * i) * ldb + (kt + 1) * 64) + voB);
;             }
;             __builtin_amdgcn_s_setprio(1);
; #pragma unroll 2
;             for (int ks = 0; ks < 4; ++ks) {
;                 bf16x8 af[2], bfr[4];
;                 const unsigned xo = (c0 ^ (unsigned)(2 * ks)) << 4;
; #pragma unroll
;                 for (int i = 0; i < 2; ++i) af[i] = *(const bf16x8*)(lds + (roA + xo) + i * 4096);
; #pragma unroll
;                 for (int j = 0; j < 4; ++j) bfr[j] = *(const bf16x8*)(lds + (roB + xo) + j * 4096);
; #pragma unroll
;                 for (int i = 0; i < 2; ++i)
; #pragma unroll
;                     for (int j = 0; j < 4; ++j) acc[i][j] = MFMA32(af[i], bfr[j], acc[i][j]);
;             }
;             __builtin_amdgcn_s_setprio(0);
;             __syncthreads();
.LBB0_871:
	s_mov_b32 s0, s5
	s_add_i32 s5, s5, 1
	s_cmp_lt_u32 s0, 15
	s_waitcnt vmcnt(0)
	ds_write_b128 v192, v[130:133]
	ds_write_b128 v192, v[138:141] offset:4096
	ds_write_b128 v192, v[170:173] offset:8192
	ds_write_b128 v192, v[134:137] offset:12288
	ds_write_b128 v192, v[174:177] offset:16384
	ds_write_b128 v192, v[166:169] offset:20480
	ds_write_b128 v192, v[162:165] offset:24576
	ds_write_b128 v192, v[158:161] offset:28672
	ds_write_b128 v192, v[154:157] offset:32768
	ds_write_b128 v192, v[150:153] offset:36864
	ds_write_b128 v192, v[146:149] offset:40960
	ds_write_b128 v192, v[142:145] offset:45056
	s_waitcnt lgkmcnt(0)
	s_barrier
	s_cbranch_scc0 .LBB0_873
	s_lshl_b32 s22, s5, 7
	s_mov_b32 s23, 0
	s_setprio 1
	v_xor_b32_e32 v1, 0, v187
	v_add_u32_e32 v193, v188, v1
	v_add_u32_e32 v1, v189, v1
	ds_read_b128 v[194:197], v193
	ds_read_b128 v[198:201], v1 offset:16384
	ds_read_b128 v[202:205], v193 offset:4096
	ds_read_b128 v[206:209], v1 offset:20480
	ds_read_b128 v[210:213], v1 offset:24576
	ds_read_b128 v[218:221], v1 offset:28672
	s_waitcnt lgkmcnt(4)
	v_mfma_f32_32x32x16_bf16 v[114:129], v[194:197], v[198:201], v[114:129]
	v_lshl_add_u64 v[222:223], v[182:183], 0, s[22:23]
	global_load_dwordx4 v[130:133], v[222:223], off
	s_add_u32 s22, s22, 0x10000
	s_mov_b32 s7, 32
	v_xor_b32_e32 v1, s7, v187
	v_add_u32_e32 v193, v188, v1
	v_add_u32_e32 v1, v189, v1
	s_waitcnt lgkmcnt(2)
	v_mfma_f32_32x32x16_bf16 v[98:113], v[194:197], v[206:209], v[98:113]
	s_waitcnt lgkmcnt(1)
	v_mfma_f32_32x32x16_bf16 v[82:97], v[194:197], v[210:213], v[82:97]
	v_lshl_add_u64 v[224:225], v[182:183], 0, s[22:23]
	global_load_dwordx4 v[138:141], v[224:225], off
	s_add_u32 s22, s22, 0x10000
	s_waitcnt lgkmcnt(0)
	v_mfma_f32_32x32x16_bf16 v[66:81], v[194:197], v[218:221], v[66:81]
	v_mfma_f32_32x32x16_bf16 v[50:65], v[202:205], v[198:201], v[50:65]
	v_lshl_add_u64 v[226:227], v[182:183], 0, s[22:23]
	global_load_dwordx4 v[170:173], v[226:227], off
	s_add_u32 s22, s22, 0x10000
	v_mfma_f32_32x32x16_bf16 v[34:49], v[202:205], v[206:209], v[34:49]
	v_mfma_f32_32x32x16_bf16 v[18:33], v[202:205], v[210:213], v[18:33]
	v_lshl_add_u64 v[222:223], v[182:183], 0, s[22:23]
	global_load_dwordx4 v[134:137], v[222:223], off
	s_sub_u32 s22, s22, 0x30000
	v_mfma_f32_32x32x16_bf16 v[2:17], v[202:205], v[218:221], v[2:17]
	ds_read_b128 v[194:197], v193
	ds_read_b128 v[198:201], v1 offset:16384
	ds_read_b128 v[202:205], v193 offset:4096
	ds_read_b128 v[206:209], v1 offset:20480
	ds_read_b128 v[210:213], v1 offset:24576
	ds_read_b128 v[218:221], v1 offset:28672
	s_waitcnt lgkmcnt(4)
	v_mfma_f32_32x32x16_bf16 v[114:129], v[194:197], v[198:201], v[114:129]
	v_lshl_add_u64 v[224:225], v[184:185], 0, s[22:23]
	global_load_dwordx4 v[174:177], v[224:225], off
	s_add_u32 s22, s22, 0x10000
	s_waitcnt lgkmcnt(2)
	v_mfma_f32_32x32x16_bf16 v[98:113], v[194:197], v[206:209], v[98:113]
	s_waitcnt lgkmcnt(1)
	v_mfma_f32_32x32x16_bf16 v[82:97], v[194:197], v[210:213], v[82:97]
	v_lshl_add_u64 v[226:227], v[184:185], 0, s[22:23]
	global_load_dwordx4 v[166:169], v[226:227], off
	s_add_u32 s22, s22, 0x10000
	s_waitcnt lgkmcnt(0)
	v_mfma_f32_32x32x16_bf16 v[66:81], v[194:197], v[218:221], v[66:81]
	v_mfma_f32_32x32x16_bf16 v[50:65], v[202:205], v[198:201], v[50:65]
	v_lshl_add_u64 v[222:223], v[184:185], 0, s[22:23]
	global_load_dwordx4 v[162:165], v[222:223], off
	s_add_u32 s22, s22, 0x10000
	v_mfma_f32_32x32x16_bf16 v[34:49], v[202:205], v[206:209], v[34:49]
	v_mfma_f32_32x32x16_bf16 v[18:33], v[202:205], v[210:213], v[18:33]
	v_lshl_add_u64 v[224:225], v[184:185], 0, s[22:23]
	global_load_dwordx4 v[158:161], v[224:225], off
	s_add_u32 s22, s22, 0x10000
	v_mfma_f32_32x32x16_bf16 v[2:17], v[202:205], v[218:221], v[2:17]
	v_xor_b32_e32 v1, 64, v187
	v_add_u32_e32 v193, v188, v1
	v_add_u32_e32 v1, v189, v1
	ds_read_b128 v[194:197], v193
	ds_read_b128 v[198:201], v1 offset:16384
	ds_read_b128 v[202:205], v193 offset:4096
	ds_read_b128 v[206:209], v1 offset:20480
	ds_read_b128 v[210:213], v1 offset:24576
	ds_read_b128 v[218:221], v1 offset:28672
	s_waitcnt lgkmcnt(4)
	v_mfma_f32_32x32x16_bf16 v[114:129], v[194:197], v[198:201], v[114:129]
	v_lshl_add_u64 v[226:227], v[184:185], 0, s[22:23]
	global_load_dwordx4 v[154:157], v[226:227], off
	s_add_u32 s22, s22, 0x10000
	s_mov_b32 s7, 96
	v_xor_b32_e32 v1, s7, v187
	v_add_u32_e32 v193, v188, v1
	v_add_u32_e32 v1, v189, v1
	s_waitcnt lgkmcnt(2)
	v_mfma_f32_32x32x16_bf16 v[98:113], v[194:197], v[206:209], v[98:113]
	s_waitcnt lgkmcnt(1)
	v_mfma_f32_32x32x16_bf16 v[82:97], v[194:197], v[210:213], v[82:97]
	v_lshl_add_u64 v[222:223], v[184:185], 0, s[22:23]
	global_load_dwordx4 v[150:153], v[222:223], off
	s_add_u32 s22, s22, 0x10000
	s_waitcnt lgkmcnt(0)
	v_mfma_f32_32x32x16_bf16 v[66:81], v[194:197], v[218:221], v[66:81]
	v_mfma_f32_32x32x16_bf16 v[50:65], v[202:205], v[198:201], v[50:65]
	v_lshl_add_u64 v[224:225], v[184:185], 0, s[22:23]
	global_load_dwordx4 v[146:149], v[224:225], off
	s_add_u32 s22, s22, 0x10000
	v_mfma_f32_32x32x16_bf16 v[34:49], v[202:205], v[206:209], v[34:49]
	v_mfma_f32_32x32x16_bf16 v[18:33], v[202:205], v[210:213], v[18:33]
	v_lshl_add_u64 v[226:227], v[184:185], 0, s[22:23]
	global_load_dwordx4 v[142:145], v[226:227], off
	v_mfma_f32_32x32x16_bf16 v[2:17], v[202:205], v[218:221], v[2:17]
	ds_read_b128 v[194:197], v193
	ds_read_b128 v[198:201], v1 offset:16384
	ds_read_b128 v[202:205], v193 offset:4096
	ds_read_b128 v[206:209], v1 offset:20480
	ds_read_b128 v[210:213], v1 offset:24576
	ds_read_b128 v[218:221], v1 offset:28672
	s_waitcnt lgkmcnt(4)
	v_mfma_f32_32x32x16_bf16 v[114:129], v[194:197], v[198:201], v[114:129]
	s_waitcnt lgkmcnt(2)
	v_mfma_f32_32x32x16_bf16 v[98:113], v[194:197], v[206:209], v[98:113]
	s_waitcnt lgkmcnt(1)
	v_mfma_f32_32x32x16_bf16 v[82:97], v[194:197], v[210:213], v[82:97]
	s_waitcnt lgkmcnt(0)
	v_mfma_f32_32x32x16_bf16 v[66:81], v[194:197], v[218:221], v[66:81]
	v_mfma_f32_32x32x16_bf16 v[50:65], v[202:205], v[198:201], v[50:65]
	v_mfma_f32_32x32x16_bf16 v[34:49], v[202:205], v[206:209], v[34:49]
	v_mfma_f32_32x32x16_bf16 v[18:33], v[202:205], v[210:213], v[18:33]
	v_mfma_f32_32x32x16_bf16 v[2:17], v[202:205], v[218:221], v[2:17]
	s_branch .Lkint_done_874

; DI unsigned swz(int row, int chunk) { return (unsigned)row * 128u + (unsigned)((chunk ^ ((row >> 1) & 7)) << 4); }
; #define MFMA32(a, b, c) __builtin_amdgcn_mfma_f32_32x32x16_bf16((a), (b), (c), 0, 0, 0)
;     ...
;         for (int kt = 0; kt < nk; ++kt) {
; #pragma unroll
;             for (int i = 0; i < 4; ++i) *(u32x4*)(lds + swz(lr + 32 * i, lc)) = ra[i];
; #pragma unroll
;             for (int i = 0; i < 8; ++i) *(u32x4*)(lds + 16384 + swz(lr + 32 * i, lc)) = rb[i];
;             __syncthreads();
;             if (kt + 1 < nk) {
; #pragma unroll
;                 for (int i = 0; i < 4; ++i) ra[i] = *(const u32x4*)((Au + (size_t)(32 * i) * lda + (kt + 1) * 64) + voA);
; #pragma unroll
;                 for (int i = 0; i < 8; ++i) rb[i] = *(const u32x4*)((Bu + (size_t)(32 * i) * ldb + (kt + 1) * 64) + voB);
;             }
;             __builtin_amdgcn_s_setprio(1);
; #pragma unroll 2
;             for (int ks = 0; ks < 4; ++ks) {
;                 bf16x8 af[2], bfr[4];
;                 const unsigned xo = (c0 ^ (unsigned)(2 * ks)) << 4;
; #pragma unroll
;                 for (int i = 0; i < 2; ++i) af[i] = *(const bf16x8*)(lds + (roA + xo) + i * 4096);
; #pragma unroll
;                 for (int j = 0; j < 4; ++j) bfr[j] = *(const bf16x8*)(lds + (roB + xo) + j * 4096);
; #pragma unroll
;                 for (int i = 0; i < 2; ++i)
; #pragma unroll
;                     for (int j = 0; j < 4; ++j) acc[i][j] = MFMA32(af[i], bfr[j], acc[i][j]);
;             }
;             __builtin_amdgcn_s_setprio(0);
;             __syncthreads();
.LBB0_1252:
	s_mov_b32 s4, s9
	s_add_i32 s9, s9, 1
	s_cmp_lt_u32 s4, 15
	s_waitcnt vmcnt(0)
	ds_write_b128 v192, v[130:133]
	ds_write_b128 v192, v[138:141] offset:4096
	ds_write_b128 v192, v[170:173] offset:8192
	ds_write_b128 v192, v[134:137] offset:12288
	ds_write_b128 v192, v[174:177] offset:16384
	ds_write_b128 v192, v[166:169] offset:20480
	ds_write_b128 v192, v[162:165] offset:24576
	ds_write_b128 v192, v[158:161] offset:28672
	ds_write_b128 v192, v[154:157] offset:32768
	ds_write_b128 v192, v[150:153] offset:36864
	ds_write_b128 v192, v[146:149] offset:40960
	ds_write_b128 v192, v[142:145] offset:45056
	s_waitcnt lgkmcnt(0)
	s_barrier
	s_cbranch_scc0 .LBB0_1254
	s_lshl_b32 s18, s9, 7
	s_mov_b32 s19, 0
	s_setprio 1
	v_xor_b32_e32 v1, 0, v187
	v_add_u32_e32 v193, v188, v1
	v_add_u32_e32 v1, v189, v1
	ds_read_b128 v[194:197], v193
	ds_read_b128 v[198:201], v1 offset:16384
	ds_read_b128 v[202:205], v193 offset:4096
	ds_read_b128 v[206:209], v1 offset:20480
	ds_read_b128 v[210:213], v1 offset:24576
	ds_read_b128 v[218:221], v1 offset:28672
	s_waitcnt lgkmcnt(4)
	v_mfma_f32_32x32x16_bf16 v[114:129], v[194:197], v[198:201], v[114:129]
	v_lshl_add_u64 v[222:223], v[182:183], 0, s[18:19]
	global_load_dwordx4 v[130:133], v[222:223], off
	s_add_u32 s18, s18, 0x10000
	s_mov_b32 s11, 32
	v_xor_b32_e32 v1, s11, v187
	v_add_u32_e32 v193, v188, v1
	v_add_u32_e32 v1, v189, v1
	s_waitcnt lgkmcnt(2)
	v_mfma_f32_32x32x16_bf16 v[82:97], v[194:197], v[206:209], v[82:97]
	s_waitcnt lgkmcnt(1)
	v_mfma_f32_32x32x16_bf16 v[50:65], v[194:197], v[210:213], v[50:65]
	v_lshl_add_u64 v[224:225], v[182:183], 0, s[18:19]
	global_load_dwordx4 v[138:141], v[224:225], off
	s_add_u32 s18, s18, 0x10000
	s_waitcnt lgkmcnt(0)
	v_mfma_f32_32x32x16_bf16 v[18:33], v[194:197], v[218:221], v[18:33]
	v_mfma_f32_32x32x16_bf16 v[98:113], v[202:205], v[198:201], v[98:113]
	v_lshl_add_u64 v[226:227], v[182:183], 0, s[18:19]
	global_load_dwordx4 v[170:173], v[226:227], off
	s_add_u32 s18, s18, 0x10000
	v_mfma_f32_32x32x16_bf16 v[66:81], v[202:205], v[206:209], v[66:81]
	v_mfma_f32_32x32x16_bf16 v[34:49], v[202:205], v[210:213], v[34:49]
	v_lshl_add_u64 v[222:223], v[182:183], 0, s[18:19]
	global_load_dwordx4 v[134:137], v[222:223], off
	s_sub_u32 s18, s18, 0x30000
	v_mfma_f32_32x32x16_bf16 v[2:17], v[202:205], v[218:221], v[2:17]
	ds_read_b128 v[194:197], v193
	ds_read_b128 v[198:201], v1 offset:16384
	ds_read_b128 v[202:205], v193 offset:4096
	ds_read_b128 v[206:209], v1 offset:20480
	ds_read_b128 v[210:213], v1 offset:24576
	ds_read_b128 v[218:221], v1 offset:28672
	s_waitcnt lgkmcnt(4)
	v_mfma_f32_32x32x16_bf16 v[114:129], v[194:197], v[198:201], v[114:129]
	v_lshl_add_u64 v[224:225], v[184:185], 0, s[18:19]
	global_load_dwordx4 v[174:177], v[224:225], off
	s_add_u32 s18, s18, 0x10000
	s_waitcnt lgkmcnt(2)
	v_mfma_f32_32x32x16_bf16 v[82:97], v[194:197], v[206:209], v[82:97]
	s_waitcnt lgkmcnt(1)
	v_mfma_f32_32x32x16_bf16 v[50:65], v[194:197], v[210:213], v[50:65]
	v_lshl_add_u64 v[226:227], v[184:185], 0, s[18:19]
	global_load_dwordx4 v[166:169], v[226:227], off
	s_add_u32 s18, s18, 0x10000
	s_waitcnt lgkmcnt(0)
	v_mfma_f32_32x32x16_bf16 v[18:33], v[194:197], v[218:221], v[18:33]
	v_mfma_f32_32x32x16_bf16 v[98:113], v[202:205], v[198:201], v[98:113]
	v_lshl_add_u64 v[222:223], v[184:185], 0, s[18:19]
	global_load_dwordx4 v[162:165], v[222:223], off
	s_add_u32 s18, s18, 0x10000
	v_mfma_f32_32x32x16_bf16 v[66:81], v[202:205], v[206:209], v[66:81]
	v_mfma_f32_32x32x16_bf16 v[34:49], v[202:205], v[210:213], v[34:49]
	v_lshl_add_u64 v[224:225], v[184:185], 0, s[18:19]
	global_load_dwordx4 v[158:161], v[224:225], off
	s_add_u32 s18, s18, 0x10000
	v_mfma_f32_32x32x16_bf16 v[2:17], v[202:205], v[218:221], v[2:17]
	v_xor_b32_e32 v1, 64, v187
	v_add_u32_e32 v193, v188, v1
	v_add_u32_e32 v1, v189, v1
	ds_read_b128 v[194:197], v193
	ds_read_b128 v[198:201], v1 offset:16384
	ds_read_b128 v[202:205], v193 offset:4096
	ds_read_b128 v[206:209], v1 offset:20480
	ds_read_b128 v[210:213], v1 offset:24576
	ds_read_b128 v[218:221], v1 offset:28672
	s_waitcnt lgkmcnt(4)
	v_mfma_f32_32x32x16_bf16 v[114:129], v[194:197], v[198:201], v[114:129]
	v_lshl_add_u64 v[226:227], v[184:185], 0, s[18:19]
	global_load_dwordx4 v[154:157], v[226:227], off
	s_add_u32 s18, s18, 0x10000
	s_mov_b32 s11, 96
	v_xor_b32_e32 v1, s11, v187
	v_add_u32_e32 v193, v188, v1
	v_add_u32_e32 v1, v189, v1
	s_waitcnt lgkmcnt(2)
	v_mfma_f32_32x32x16_bf16 v[82:97], v[194:197], v[206:209], v[82:97]
	s_waitcnt lgkmcnt(1)
	v_mfma_f32_32x32x16_bf16 v[50:65], v[194:197], v[210:213], v[50:65]
	v_lshl_add_u64 v[222:223], v[184:185], 0, s[18:19]
	global_load_dwordx4 v[150:153], v[222:223], off
	s_add_u32 s18, s18, 0x10000
	s_waitcnt lgkmcnt(0)
	v_mfma_f32_32x32x16_bf16 v[18:33], v[194:197], v[218:221], v[18:33]
	v_mfma_f32_32x32x16_bf16 v[98:113], v[202:205], v[198:201], v[98:113]
	v_lshl_add_u64 v[224:225], v[184:185], 0, s[18:19]
	global_load_dwordx4 v[146:149], v[224:225], off
	s_add_u32 s18, s18, 0x10000
	v_mfma_f32_32x32x16_bf16 v[66:81], v[202:205], v[206:209], v[66:81]
	v_mfma_f32_32x32x16_bf16 v[34:49], v[202:205], v[210:213], v[34:49]
	v_lshl_add_u64 v[226:227], v[184:185], 0, s[18:19]
	global_load_dwordx4 v[142:145], v[226:227], off
	v_mfma_f32_32x32x16_bf16 v[2:17], v[202:205], v[218:221], v[2:17]
	ds_read_b128 v[194:197], v193
	ds_read_b128 v[198:201], v1 offset:16384
	ds_read_b128 v[202:205], v193 offset:4096
	ds_read_b128 v[206:209], v1 offset:20480
	ds_read_b128 v[210:213], v1 offset:24576
	ds_read_b128 v[218:221], v1 offset:28672
	s_waitcnt lgkmcnt(4)
	v_mfma_f32_32x32x16_bf16 v[114:129], v[194:197], v[198:201], v[114:129]
	s_waitcnt lgkmcnt(2)
	v_mfma_f32_32x32x16_bf16 v[82:97], v[194:197], v[206:209], v[82:97]
	s_waitcnt lgkmcnt(1)
	v_mfma_f32_32x32x16_bf16 v[50:65], v[194:197], v[210:213], v[50:65]
	s_waitcnt lgkmcnt(0)
	v_mfma_f32_32x32x16_bf16 v[18:33], v[194:197], v[218:221], v[18:33]
	v_mfma_f32_32x32x16_bf16 v[98:113], v[202:205], v[198:201], v[98:113]
	v_mfma_f32_32x32x16_bf16 v[66:81], v[202:205], v[206:209], v[66:81]
	v_mfma_f32_32x32x16_bf16 v[34:49], v[202:205], v[210:213], v[34:49]
	v_mfma_f32_32x32x16_bf16 v[2:17], v[202:205], v[218:221], v[2:17]
	s_branch .Lkint_done_1255

; DI unsigned swz(int row, int chunk) { return (unsigned)row * 128u + (unsigned)((chunk ^ ((row >> 1) & 7)) << 4); }
; #define MFMA32(a, b, c) __builtin_amdgcn_mfma_f32_32x32x16_bf16((a), (b), (c), 0, 0, 0)
;     ...
;         for (int kt = 0; kt < nk; ++kt) {
; #pragma unroll
;             for (int i = 0; i < 4; ++i) *(u32x4*)(lds + swz(lr + 32 * i, lc)) = ra[i];
; #pragma unroll
;             for (int i = 0; i < 8; ++i) *(u32x4*)(lds + 16384 + swz(lr + 32 * i, lc)) = rb[i];
;             __syncthreads();
;             if (kt + 1 < nk) {
; #pragma unroll
;                 for (int i = 0; i < 4; ++i) ra[i] = *(const u32x4*)((Au + (size_t)(32 * i) * lda + (kt + 1) * 64) + voA);
; #pragma unroll
;                 for (int i = 0; i < 8; ++i) rb[i] = *(const u32x4*)((Bu + (size_t)(32 * i) * ldb + (kt + 1) * 64) + voB);
;             }
;             __builtin_amdgcn_s_setprio(1);
; #pragma unroll 2
;             for (int ks = 0; ks < 4; ++ks) {
;                 bf16x8 af[2], bfr[4];
;                 const unsigned xo = (c0 ^ (unsigned)(2 * ks)) << 4;
; #pragma unroll
;                 for (int i = 0; i < 2; ++i) af[i] = *(const bf16x8*)(lds + (roA + xo) + i * 4096);
; #pragma unroll
;                 for (int j = 0; j < 4; ++j) bfr[j] = *(const bf16x8*)(lds + (roB + xo) + j * 4096);
; #pragma unroll
;                 for (int i = 0; i < 2; ++i)
; #pragma unroll
;                     for (int j = 0; j < 4; ++j) acc[i][j] = MFMA32(af[i], bfr[j], acc[i][j]);
;             }
;             __builtin_amdgcn_s_setprio(0);
;             __syncthreads();
.LBB0_1338:
	s_mov_b32 s4, s7
	s_add_i32 s7, s7, 1
	s_cmp_lg_u32 s4, 15
	s_waitcnt vmcnt(9)
	ds_write_b128 v206, v[148:151]
	ds_write_b128 v206, v[144:147] offset:4096
	ds_write_b128 v206, v[152:155] offset:8192
	s_waitcnt vmcnt(7)
	ds_write_b128 v206, v[156:159] offset:12288
	ds_write_b128 v206, v[160:163] offset:16384
	s_waitcnt vmcnt(6)
	ds_write_b128 v206, v[164:167] offset:20480
	s_waitcnt vmcnt(5)
	ds_write_b128 v206, v[168:171] offset:24576
	s_waitcnt vmcnt(4)
	ds_write_b128 v206, v[172:175] offset:28672
	s_waitcnt vmcnt(3)
	ds_write_b128 v206, v[176:179] offset:32768
	s_waitcnt vmcnt(2)
	ds_write_b128 v206, v[180:183] offset:36864
	s_waitcnt vmcnt(1)
	ds_write_b128 v206, v[184:187] offset:40960
	s_waitcnt vmcnt(0)
	ds_write_b128 v206, v[188:191] offset:45056
	s_waitcnt lgkmcnt(0)
	s_barrier
	s_cbranch_scc0 .LBB0_1340
	s_lshl_b32 s18, s7, 7
	s_mov_b32 s19, 0
	s_setprio 1
	v_xor_b32_e32 v1, 0, v201
	v_add_u32_e32 v10, v202, v1
	v_add_u32_e32 v1, v203, v1
	ds_read_b128 v[2:5], v10
	ds_read_b128 v[6:9], v1 offset:16384
	ds_read_b128 v[10:13], v10 offset:4096
	ds_read_b128 v[208:211], v1 offset:20480
	ds_read_b128 v[212:215], v1 offset:24576
	ds_read_b128 v[218:221], v1 offset:28672
	s_waitcnt lgkmcnt(4)
	v_mfma_f32_32x32x16_bf16 v[128:143], v[2:5], v[6:9], v[128:143]
	v_lshl_add_u64 v[222:223], v[196:197], 0, s[18:19]
	global_load_dwordx4 v[148:151], v[222:223], off
	s_add_u32 s18, s18, 0x10000
	s_mov_b32 s9, 32
	v_xor_b32_e32 v1, s9, v201
	v_add_u32_e32 v14, v202, v1
	v_add_u32_e32 v1, v203, v1
	s_waitcnt lgkmcnt(2)
	v_mfma_f32_32x32x16_bf16 v[112:127], v[2:5], v[208:211], v[112:127]
	s_waitcnt lgkmcnt(1)
	v_mfma_f32_32x32x16_bf16 v[48:63], v[2:5], v[212:215], v[48:63]
	v_lshl_add_u64 v[224:225], v[196:197], 0, s[18:19]
	global_load_dwordx4 v[144:147], v[224:225], off
	s_add_u32 s18, s18, 0x10000
	s_waitcnt lgkmcnt(0)
	v_mfma_f32_32x32x16_bf16 v[64:79], v[2:5], v[218:221], v[64:79]
	v_mfma_f32_32x32x16_bf16 v[80:95], v[10:13], v[6:9], v[80:95]
	v_lshl_add_u64 v[226:227], v[196:197], 0, s[18:19]
	global_load_dwordx4 v[152:155], v[226:227], off
	s_add_u32 s18, s18, 0x10000
	v_mfma_f32_32x32x16_bf16 v[96:111], v[10:13], v[208:211], v[96:111]
	v_mfma_f32_32x32x16_bf16 v[16:31], v[10:13], v[212:215], v[16:31]
	v_lshl_add_u64 v[222:223], v[196:197], 0, s[18:19]
	global_load_dwordx4 v[156:159], v[222:223], off
	s_sub_u32 s18, s18, 0x30000
	v_mfma_f32_32x32x16_bf16 v[32:47], v[10:13], v[218:221], v[32:47]
	ds_read_b128 v[2:5], v14
	ds_read_b128 v[6:9], v1 offset:16384
	ds_read_b128 v[10:13], v14 offset:4096
	ds_read_b128 v[208:211], v1 offset:20480
	ds_read_b128 v[212:215], v1 offset:24576
	ds_read_b128 v[218:221], v1 offset:28672
	s_waitcnt lgkmcnt(4)
	v_mfma_f32_32x32x16_bf16 v[128:143], v[2:5], v[6:9], v[128:143]
	v_lshl_add_u64 v[224:225], v[198:199], 0, s[18:19]
	global_load_dwordx4 v[160:163], v[224:225], off
	s_add_u32 s18, s18, 0x10000
	s_waitcnt lgkmcnt(2)
	v_mfma_f32_32x32x16_bf16 v[112:127], v[2:5], v[208:211], v[112:127]
	s_waitcnt lgkmcnt(1)
	v_mfma_f32_32x32x16_bf16 v[48:63], v[2:5], v[212:215], v[48:63]
	v_lshl_add_u64 v[226:227], v[198:199], 0, s[18:19]
	global_load_dwordx4 v[164:167], v[226:227], off
	s_add_u32 s18, s18, 0x10000
	s_waitcnt lgkmcnt(0)
	v_mfma_f32_32x32x16_bf16 v[64:79], v[2:5], v[218:221], v[64:79]
	v_mfma_f32_32x32x16_bf16 v[80:95], v[10:13], v[6:9], v[80:95]
	v_lshl_add_u64 v[222:223], v[198:199], 0, s[18:19]
	global_load_dwordx4 v[168:171], v[222:223], off
	s_add_u32 s18, s18, 0x10000
	v_mfma_f32_32x32x16_bf16 v[96:111], v[10:13], v[208:211], v[96:111]
	v_mfma_f32_32x32x16_bf16 v[16:31], v[10:13], v[212:215], v[16:31]
	v_lshl_add_u64 v[224:225], v[198:199], 0, s[18:19]
	global_load_dwordx4 v[172:175], v[224:225], off
	s_add_u32 s18, s18, 0x10000
	v_mfma_f32_32x32x16_bf16 v[32:47], v[10:13], v[218:221], v[32:47]
	v_xor_b32_e32 v1, 64, v201
	v_add_u32_e32 v10, v202, v1
	v_add_u32_e32 v1, v203, v1
	ds_read_b128 v[2:5], v10
	ds_read_b128 v[6:9], v1 offset:16384
	ds_read_b128 v[10:13], v10 offset:4096
	ds_read_b128 v[208:211], v1 offset:20480
	ds_read_b128 v[212:215], v1 offset:24576
	ds_read_b128 v[218:221], v1 offset:28672
	s_waitcnt lgkmcnt(4)
	v_mfma_f32_32x32x16_bf16 v[128:143], v[2:5], v[6:9], v[128:143]
	v_lshl_add_u64 v[226:227], v[198:199], 0, s[18:19]
	global_load_dwordx4 v[176:179], v[226:227], off
	s_add_u32 s18, s18, 0x10000
	s_mov_b32 s9, 96
	v_xor_b32_e32 v1, s9, v201
	v_add_u32_e32 v14, v202, v1
	v_add_u32_e32 v1, v203, v1
	s_waitcnt lgkmcnt(2)
	v_mfma_f32_32x32x16_bf16 v[112:127], v[2:5], v[208:211], v[112:127]
	s_waitcnt lgkmcnt(1)
	v_mfma_f32_32x32x16_bf16 v[48:63], v[2:5], v[212:215], v[48:63]
	v_lshl_add_u64 v[222:223], v[198:199], 0, s[18:19]
	global_load_dwordx4 v[180:183], v[222:223], off
	s_add_u32 s18, s18, 0x10000
	s_waitcnt lgkmcnt(0)
	v_mfma_f32_32x32x16_bf16 v[64:79], v[2:5], v[218:221], v[64:79]
	v_mfma_f32_32x32x16_bf16 v[80:95], v[10:13], v[6:9], v[80:95]
	v_lshl_add_u64 v[224:225], v[198:199], 0, s[18:19]
	global_load_dwordx4 v[184:187], v[224:225], off
	s_add_u32 s18, s18, 0x10000
	v_mfma_f32_32x32x16_bf16 v[96:111], v[10:13], v[208:211], v[96:111]
	v_mfma_f32_32x32x16_bf16 v[16:31], v[10:13], v[212:215], v[16:31]
	v_lshl_add_u64 v[226:227], v[198:199], 0, s[18:19]
	global_load_dwordx4 v[188:191], v[226:227], off
	v_mfma_f32_32x32x16_bf16 v[32:47], v[10:13], v[218:221], v[32:47]
	ds_read_b128 v[2:5], v14
	ds_read_b128 v[6:9], v1 offset:16384
	ds_read_b128 v[10:13], v14 offset:4096
	ds_read_b128 v[208:211], v1 offset:20480
	ds_read_b128 v[212:215], v1 offset:24576
	ds_read_b128 v[218:221], v1 offset:28672
	s_waitcnt lgkmcnt(4)
	v_mfma_f32_32x32x16_bf16 v[128:143], v[2:5], v[6:9], v[128:143]
	s_waitcnt lgkmcnt(2)
	v_mfma_f32_32x32x16_bf16 v[112:127], v[2:5], v[208:211], v[112:127]
	s_waitcnt lgkmcnt(1)
	v_mfma_f32_32x32x16_bf16 v[48:63], v[2:5], v[212:215], v[48:63]
	s_waitcnt lgkmcnt(0)
	v_mfma_f32_32x32x16_bf16 v[64:79], v[2:5], v[218:221], v[64:79]
	v_mfma_f32_32x32x16_bf16 v[80:95], v[10:13], v[6:9], v[80:95]
	v_mfma_f32_32x32x16_bf16 v[96:111], v[10:13], v[208:211], v[96:111]
	v_mfma_f32_32x32x16_bf16 v[16:31], v[10:13], v[212:215], v[16:31]
	v_mfma_f32_32x32x16_bf16 v[32:47], v[10:13], v[218:221], v[32:47]
	s_branch .Lkint_done_1341

; DI unsigned swz(int row, int chunk) { return (unsigned)row * 128u + (unsigned)((chunk ^ ((row >> 1) & 7)) << 4); }
; #define MFMA32(a, b, c) __builtin_amdgcn_mfma_f32_32x32x16_bf16((a), (b), (c), 0, 0, 0)
;     ...
;         for (int kt = 0; kt < nk; ++kt) {
; #pragma unroll
;             for (int i = 0; i < 4; ++i) *(u32x4*)(lds + swz(lr + 32 * i, lc)) = ra[i];
; #pragma unroll
;             for (int i = 0; i < 8; ++i) *(u32x4*)(lds + 16384 + swz(lr + 32 * i, lc)) = rb[i];
;             __syncthreads();
;             if (kt + 1 < nk) {
; #pragma unroll
;                 for (int i = 0; i < 4; ++i) ra[i] = *(const u32x4*)((Au + (size_t)(32 * i) * lda + (kt + 1) * 64) + voA);
; #pragma unroll
;                 for (int i = 0; i < 8; ++i) rb[i] = *(const u32x4*)((Bu + (size_t)(32 * i) * ldb + (kt + 1) * 64) + voB);
;             }
;             __builtin_amdgcn_s_setprio(1);
; #pragma unroll 2
;             for (int ks = 0; ks < 4; ++ks) {
;                 bf16x8 af[2], bfr[4];
;                 const unsigned xo = (c0 ^ (unsigned)(2 * ks)) << 4;
; #pragma unroll
;                 for (int i = 0; i < 2; ++i) af[i] = *(const bf16x8*)(lds + (roA + xo) + i * 4096);
; #pragma unroll
;                 for (int j = 0; j < 4; ++j) bfr[j] = *(const bf16x8*)(lds + (roB + xo) + j * 4096);
; #pragma unroll
;                 for (int i = 0; i < 2; ++i)
; #pragma unroll
;                     for (int j = 0; j < 4; ++j) acc[i][j] = MFMA32(af[i], bfr[j], acc[i][j]);
;             }
;             __builtin_amdgcn_s_setprio(0);
;             __syncthreads();
.LBB0_1384:
	s_mov_b32 s0, s59
	s_add_i32 s59, s59, 1
	s_cmp_lt_u32 s0, 43
	s_waitcnt vmcnt(0)
	ds_write_b128 v193, v[130:133]
	ds_write_b128 v193, v[138:141] offset:4096
	ds_write_b128 v193, v[170:173] offset:8192
	ds_write_b128 v193, v[134:137] offset:12288
	ds_write_b128 v193, v[174:177] offset:16384
	ds_write_b128 v193, v[166:169] offset:20480
	ds_write_b128 v193, v[162:165] offset:24576
	ds_write_b128 v193, v[158:161] offset:28672
	ds_write_b128 v193, v[154:157] offset:32768
	ds_write_b128 v193, v[150:153] offset:36864
	ds_write_b128 v193, v[146:149] offset:40960
	ds_write_b128 v193, v[142:145] offset:45056
	s_waitcnt lgkmcnt(0)
	s_barrier
	s_cbranch_scc0 .LBB0_1386
	s_lshl_b32 s60, s59, 7
	s_mov_b32 s61, 0
	s_setprio 1
	v_xor_b32_e32 v1, 0, v187
	v_add_u32_e32 v202, v188, v1
	v_add_u32_e32 v1, v189, v1
	ds_read_b128 v[194:197], v202
	ds_read_b128 v[198:201], v1 offset:16384
	ds_read_b128 v[202:205], v202 offset:4096
	ds_read_b128 v[206:209], v1 offset:20480
	ds_read_b128 v[210:213], v1 offset:24576
	ds_read_b128 v[218:221], v1 offset:28672
	s_waitcnt lgkmcnt(4)
	v_mfma_f32_32x32x16_bf16 v[114:129], v[194:197], v[198:201], v[114:129]
	v_lshl_add_u64 v[222:223], v[182:183], 0, s[60:61]
	global_load_dwordx4 v[130:133], v[222:223], off
	s_add_u32 s60, s60, 0x2c000
	s_mov_b32 s18, 32
	v_xor_b32_e32 v1, s18, v187
	s_waitcnt lgkmcnt(2)
	v_mfma_f32_32x32x16_bf16 v[82:97], v[194:197], v[206:209], v[82:97]
	s_waitcnt lgkmcnt(1)
	v_mfma_f32_32x32x16_bf16 v[50:65], v[194:197], v[210:213], v[50:65]
	v_lshl_add_u64 v[224:225], v[182:183], 0, s[60:61]
	global_load_dwordx4 v[138:141], v[224:225], off
	s_add_u32 s60, s60, 0x2c000
	s_waitcnt lgkmcnt(0)
	v_mfma_f32_32x32x16_bf16 v[18:33], v[194:197], v[218:221], v[18:33]
	v_mfma_f32_32x32x16_bf16 v[98:113], v[202:205], v[198:201], v[98:113]
	v_lshl_add_u64 v[226:227], v[182:183], 0, s[60:61]
	global_load_dwordx4 v[170:173], v[226:227], off
	s_add_u32 s60, s60, 0x2c000
	v_mfma_f32_32x32x16_bf16 v[66:81], v[202:205], v[206:209], v[66:81]
	v_add_u32_e32 v206, v188, v1
	v_add_u32_e32 v1, v189, v1
	v_mfma_f32_32x32x16_bf16 v[34:49], v[202:205], v[210:213], v[34:49]
	v_lshl_add_u64 v[222:223], v[182:183], 0, s[60:61]
	global_load_dwordx4 v[134:137], v[222:223], off
	s_sub_u32 s60, s60, 0x84000
	v_mfma_f32_32x32x16_bf16 v[2:17], v[202:205], v[218:221], v[2:17]
	ds_read_b128 v[194:197], v206
	ds_read_b128 v[198:201], v1 offset:16384
	ds_read_b128 v[202:205], v206 offset:4096
	ds_read_b128 v[206:209], v1 offset:20480
	ds_read_b128 v[210:213], v1 offset:24576
	ds_read_b128 v[218:221], v1 offset:28672
	s_waitcnt lgkmcnt(4)
	v_mfma_f32_32x32x16_bf16 v[114:129], v[194:197], v[198:201], v[114:129]
	v_lshl_add_u64 v[224:225], v[184:185], 0, s[60:61]
	global_load_dwordx4 v[174:177], v[224:225], off
	s_add_u32 s60, s60, 0x2c000
	s_waitcnt lgkmcnt(2)
	v_mfma_f32_32x32x16_bf16 v[82:97], v[194:197], v[206:209], v[82:97]
	s_waitcnt lgkmcnt(1)
	v_mfma_f32_32x32x16_bf16 v[50:65], v[194:197], v[210:213], v[50:65]
	v_lshl_add_u64 v[226:227], v[184:185], 0, s[60:61]
	global_load_dwordx4 v[166:169], v[226:227], off
	s_add_u32 s60, s60, 0x2c000
	s_waitcnt lgkmcnt(0)
	v_mfma_f32_32x32x16_bf16 v[18:33], v[194:197], v[218:221], v[18:33]
	v_mfma_f32_32x32x16_bf16 v[98:113], v[202:205], v[198:201], v[98:113]
	v_lshl_add_u64 v[222:223], v[184:185], 0, s[60:61]
	global_load_dwordx4 v[162:165], v[222:223], off
	s_add_u32 s60, s60, 0x2c000
	v_mfma_f32_32x32x16_bf16 v[66:81], v[202:205], v[206:209], v[66:81]
	v_mfma_f32_32x32x16_bf16 v[34:49], v[202:205], v[210:213], v[34:49]
	v_lshl_add_u64 v[224:225], v[184:185], 0, s[60:61]
	global_load_dwordx4 v[158:161], v[224:225], off
	s_add_u32 s60, s60, 0x2c000
	v_mfma_f32_32x32x16_bf16 v[2:17], v[202:205], v[218:221], v[2:17]
	v_xor_b32_e32 v1, 64, v187
	v_add_u32_e32 v202, v188, v1
	v_add_u32_e32 v1, v189, v1
	ds_read_b128 v[194:197], v202
	ds_read_b128 v[198:201], v1 offset:16384
	ds_read_b128 v[202:205], v202 offset:4096
	ds_read_b128 v[206:209], v1 offset:20480
	ds_read_b128 v[210:213], v1 offset:24576
	ds_read_b128 v[218:221], v1 offset:28672
	s_waitcnt lgkmcnt(4)
	v_mfma_f32_32x32x16_bf16 v[114:129], v[194:197], v[198:201], v[114:129]
	v_lshl_add_u64 v[226:227], v[184:185], 0, s[60:61]
	global_load_dwordx4 v[154:157], v[226:227], off
	s_add_u32 s60, s60, 0x2c000
	s_mov_b32 s18, 96
	v_xor_b32_e32 v1, s18, v187
	s_waitcnt lgkmcnt(2)
	v_mfma_f32_32x32x16_bf16 v[82:97], v[194:197], v[206:209], v[82:97]
	s_waitcnt lgkmcnt(1)
	v_mfma_f32_32x32x16_bf16 v[50:65], v[194:197], v[210:213], v[50:65]
	v_lshl_add_u64 v[222:223], v[184:185], 0, s[60:61]
	global_load_dwordx4 v[150:153], v[222:223], off
	s_add_u32 s60, s60, 0x2c000
	s_waitcnt lgkmcnt(0)
	v_mfma_f32_32x32x16_bf16 v[18:33], v[194:197], v[218:221], v[18:33]
	v_mfma_f32_32x32x16_bf16 v[98:113], v[202:205], v[198:201], v[98:113]
	v_lshl_add_u64 v[224:225], v[184:185], 0, s[60:61]
	global_load_dwordx4 v[146:149], v[224:225], off
	s_add_u32 s60, s60, 0x2c000
	v_mfma_f32_32x32x16_bf16 v[66:81], v[202:205], v[206:209], v[66:81]
	v_add_u32_e32 v206, v188, v1
	v_add_u32_e32 v1, v189, v1
	v_mfma_f32_32x32x16_bf16 v[34:49], v[202:205], v[210:213], v[34:49]
	v_lshl_add_u64 v[226:227], v[184:185], 0, s[60:61]
	global_load_dwordx4 v[142:145], v[226:227], off
	v_mfma_f32_32x32x16_bf16 v[2:17], v[202:205], v[218:221], v[2:17]
	ds_read_b128 v[194:197], v206
	ds_read_b128 v[198:201], v1 offset:16384
	ds_read_b128 v[202:205], v206 offset:4096
	ds_read_b128 v[206:209], v1 offset:20480
	ds_read_b128 v[210:213], v1 offset:24576
	ds_read_b128 v[218:221], v1 offset:28672
	s_waitcnt lgkmcnt(4)
	v_mfma_f32_32x32x16_bf16 v[114:129], v[194:197], v[198:201], v[114:129]
	s_waitcnt lgkmcnt(2)
	v_mfma_f32_32x32x16_bf16 v[82:97], v[194:197], v[206:209], v[82:97]
	s_waitcnt lgkmcnt(1)
	v_mfma_f32_32x32x16_bf16 v[50:65], v[194:197], v[210:213], v[50:65]
	s_waitcnt lgkmcnt(0)
	v_mfma_f32_32x32x16_bf16 v[18:33], v[194:197], v[218:221], v[18:33]
	v_mfma_f32_32x32x16_bf16 v[98:113], v[202:205], v[198:201], v[98:113]
	v_mfma_f32_32x32x16_bf16 v[66:81], v[202:205], v[206:209], v[66:81]
	v_mfma_f32_32x32x16_bf16 v[34:49], v[202:205], v[210:213], v[34:49]
	v_mfma_f32_32x32x16_bf16 v[2:17], v[202:205], v[218:221], v[2:17]
	s_branch .Lkint_done_1387
